# static s_setprio 2 for waves 0-3 during the attention/GLA phase (P3), reset before the grid barrier
# speedup vs baseline: 1.0071x; 1.0071x over previous
; __global__ void __launch_bounds__(512, 2) hybrid_fwd(Params p) {
;     ...
;         if (PH(3)) { PHB
;             if (c < 128) {
;                 const int u = c;
;                     const int qb = 31 - (u >> 2), hd = u & 3, tq0 = 256 * qb + 32 * wave, t_row = tq0 + (lane & 31);
.LBB0_533:
	s_or_b64 exec, exec, s[0:1]
	v_readlane_b32 s0, v255, 0
	s_mov_b32 s70, s23
	s_mov_b32 s2, s0
	v_mov_b32_e32 v144, v234
	s_waitcnt lgkmcnt(0)
	s_barrier
	s_mov_b64 s[8:9], s[50:51]
	v_readfirstlane_b32 s15, v144
	s_ashr_i32 s3, s15, 6
	s_cmp_lt_u32 s3, 4
	s_cbranch_scc0 .Lp3_prio_skip
	s_setprio 2
.Lp3_prio_skip:
	s_cmpk_gt_i32 s2, 0x7f
	s_mov_b64 s[0:1], -1
	s_cbranch_scc1 .LBB0_536
	s_and_b64 vcc, exec, s[0:1]
	s_cbranch_vccnz .LBB0_568

; #define LAS __attribute__((address_space(3)))
; __device__ __forceinline__ unsigned xb_add(unsigned* p, unsigned v) { return __hip_atomic_fetch_add(p, v, __ATOMIC_RELAXED, __HIP_MEMORY_SCOPE_AGENT); }
; __device__ __forceinline__ unsigned xb_xcc_id() { return (unsigned)__builtin_amdgcn_s_getreg((3 << 11) | 20) & 0xFu; }
; __device__ __forceinline__ void xcd_barrier(unsigned* bar, volatile LAS unsigned* st, bool leader, unsigned G) {
;     asm volatile("s_waitcnt vmcnt(0)" ::: "memory");
;     __syncthreads();
;     if (leader) {
;         const unsigned x = xb_xcc_id();
;         __builtin_amdgcn_s_waitcnt(0);
;         unsigned nloc = st[0], nx = st[1];
;         if (nloc == 0u) { xcd_barrier_complete(bar, x, G, nloc, nx); st[0] = nloc; st[1] = nx; }
;         const unsigned old = xb_add(&bar[XB_XSUB(x)], 1u);
.LBB0_619:
	s_setprio 0
	s_waitcnt vmcnt(0)
	s_barrier
	s_mov_b64 s[0:1], exec
	v_readlane_b32 s2, v255, 24
	v_readlane_b32 s3, v255, 25
	s_and_b64 s[2:3], s[0:1], s[2:3]
	v_readlane_b32 s28, v255, 42
	v_readlane_b32 s29, v255, 43
	s_mov_b64 exec, s[2:3]
	s_cbranch_execz .LBB0_671
	v_readlane_b32 s3, v255, 34
	s_getreg_b32 s2, hwreg(HW_REG_XCC_ID, 0, 4)
	s_waitcnt vmcnt(0) expcnt(0) lgkmcnt(0)
	v_mov_b32_e32 v0, s3
	ds_read_b32 v2, v0
	v_readlane_b32 s3, v255, 35
	s_and_b32 s8, s2, 15
	s_waitcnt lgkmcnt(0)
	v_cmp_ne_u32_e32 vcc, 0, v2
	v_mov_b32_e32 v0, s3
	ds_read_b32 v0, v0
	s_cbranch_vccnz .LBB0_635
	s_mov_b32 s9, 1
	s_branch .LBB0_623
